# speedup vs baseline: 1.0054x; 1.0054x over previous
; #define PG8_STAGE(bufoff, gbase, voff) do { _Pragma("unroll") for (int _i = 0; _i < 2; ++_i) \
;         __builtin_amdgcn_global_load_lds((const unsigned*)((const char*)(gbase) + (voff)[_i]), (PG8_LAS unsigned*)(lds + (bufoff) + ldsw + _i * 8192), 16, 0, 0); } while (0)
; #define PG8_LDA(dst, b, h) do { _Pragma("unroll") for (int m = 0; m < 4; ++m) _Pragma("unroll") for (int k = 0; k < 2; ++k) dst[m][k] = *(const PG8_LAS bf16x8*)(lds + PG8_SA(b, h) + aoff + m * 2048 + k * 1024); } while (0)
; #define PG8_LDB(dst, b, h) do { _Pragma("unroll") for (int n = 0; n < 2; ++n) _Pragma("unroll") for (int k = 0; k < 2; ++k) dst[n][k] = *(const PG8_LAS bf16x8*)(lds + PG8_SB(b, h) + boff + n * 2048 + k * 1024); } while (0)
; #define PG8_MMA(ai, bj, At, Bt) do { __builtin_amdgcn_s_setprio(1); _Pragma("unroll") for (int m = 0; m < 4; ++m) _Pragma("unroll") for (int n = 0; n < 2; ++n) _Pragma("unroll") for (int k = 0; k < 2; ++k) \
;         acc[ai][bj][m][n] = __builtin_amdgcn_mfma_f32_16x16x32_bf16(Bt[n][k], At[m][k], acc[ai][bj][m][n], 0, 0, 0); __builtin_amdgcn_s_setprio(0); } while (0)
; #define PG8_WAIT_V(n) asm volatile("s_waitcnt vmcnt(" #n ")" ::: "memory")
; #define PG8_WAIT_L(n) asm volatile("s_waitcnt lgkmcnt(" #n ")" ::: "memory")
; #define PG8_BAR __builtin_amdgcn_s_barrier()
; #define PG8_SCHED __builtin_amdgcn_sched_barrier(0)
; template <class Epi, class Sched, bool ALIGN_EPI = false, bool SP2 = false>
; __device__ __forceinline__ void gemm_phase(PG8_LAS unsigned char* lds, const Gemm g, const Sched& S, const Epi& E, const int tid) {
;     ...
;             PG8_WAIT_V(8); PG8_WAIT_L(0); PG8_BAR; PG8_MMA(1, 0, At, B0); PG8_MMA(1, 1, At, B1); PG8_BAR; PG8_SCHED;
;             PG8_LDB(B0, 1, 0); PG8_LDB(B1, 1, 1); PG8_SCHED; PG8_LDA(At, 1, 0); PG8_STAGE(PG8_SA(0, 1), a2 + hstep, voffA);
;             PG8_WAIT_V(8); PG8_WAIT_L(0); PG8_BAR; PG8_MMA(0, 0, At, B0); PG8_MMA(0, 1, At, B1); PG8_BAR; PG8_SCHED;
.Lmy_wj_0:
	s_waitcnt lgkmcnt(0)
	s_barrier
	s_setprio 1
	s_waitcnt lgkmcnt(0)
	v_mfma_f32_16x16x32_bf16 v[60:63], v[138:141], v[188:191], 0
	v_mfma_f32_16x16x32_bf16 v[56:59], v[150:153], v[188:191], 0
	v_mfma_f32_16x16x32_bf16 v[44:47], v[138:141], v[208:211], 0
	v_mfma_f32_16x16x32_bf16 v[40:43], v[150:153], v[208:211], 0
	v_mfma_f32_16x16x32_bf16 v[28:31], v[138:141], v[218:221], 0
	v_mfma_f32_16x16x32_bf16 v[24:27], v[150:153], v[218:221], 0
	v_mfma_f32_16x16x32_bf16 v[12:15], v[138:141], v[226:229], 0
	v_mfma_f32_16x16x32_bf16 v[8:11], v[150:153], v[226:229], 0
	v_mfma_f32_16x16x32_bf16 v[60:63], v[146:149], v[192:195], v[60:63]
	v_mfma_f32_16x16x32_bf16 v[56:59], v[154:157], v[192:195], v[56:59]
	v_mfma_f32_16x16x32_bf16 v[44:47], v[146:149], v[214:217], v[44:47]
	v_mfma_f32_16x16x32_bf16 v[40:43], v[154:157], v[214:217], v[40:43]
	v_mfma_f32_16x16x32_bf16 v[28:31], v[146:149], v[222:225], v[28:31]
	v_mfma_f32_16x16x32_bf16 v[24:27], v[154:157], v[222:225], v[24:27]
	v_mfma_f32_16x16x32_bf16 v[12:15], v[146:149], v[230:233], v[12:15]
	v_mfma_f32_16x16x32_bf16 v[8:11], v[154:157], v[230:233], v[8:11]
	s_setprio 0
	s_setprio 1
	v_mfma_f32_16x16x32_bf16 v[52:55], v[162:165], v[188:191], 0
	v_mfma_f32_16x16x32_bf16 v[48:51], v[170:173], v[188:191], 0
	v_mfma_f32_16x16x32_bf16 v[36:39], v[162:165], v[208:211], 0
	v_mfma_f32_16x16x32_bf16 v[32:35], v[170:173], v[208:211], 0
	v_mfma_f32_16x16x32_bf16 v[20:23], v[162:165], v[218:221], 0
	v_mfma_f32_16x16x32_bf16 v[16:19], v[170:173], v[218:221], 0
	v_mfma_f32_16x16x32_bf16 v[4:7], v[162:165], v[226:229], 0
	v_mfma_f32_16x16x32_bf16 v[0:3], v[170:173], v[226:229], 0
	v_mfma_f32_16x16x32_bf16 v[52:55], v[166:169], v[192:195], v[52:55]
	v_mfma_f32_16x16x32_bf16 v[48:51], v[184:187], v[192:195], v[48:51]
	v_mfma_f32_16x16x32_bf16 v[36:39], v[166:169], v[214:217], v[36:39]
	v_mfma_f32_16x16x32_bf16 v[32:35], v[184:187], v[214:217], v[32:35]
	v_mfma_f32_16x16x32_bf16 v[20:23], v[166:169], v[222:225], v[20:23]
	v_mfma_f32_16x16x32_bf16 v[16:19], v[184:187], v[222:225], v[16:19]
	v_mfma_f32_16x16x32_bf16 v[4:7], v[166:169], v[230:233], v[4:7]
	v_mfma_f32_16x16x32_bf16 v[0:3], v[184:187], v[230:233], v[0:3]
	s_setprio 0
	s_barrier
	s_add_i32 s45, 0, 0x18000
	s_add_i32 s63, 0, 0x1c000
	v_add_u32_e32 v154, s45, v143
	v_add_u32_e32 v183, s63, v143
	ds_read_b128 v[138:141], v154
	ds_read_b128 v[146:149], v154 offset:1024
	ds_read_b128 v[150:153], v154 offset:2048
	ds_read_b128 v[154:157], v154 offset:3072
	ds_read_b128 v[162:165], v183
	ds_read_b128 v[166:169], v183 offset:1024
	ds_read_b128 v[170:173], v183 offset:2048
	ds_read_b128 v[184:187], v183 offset:3072
	s_add_u32 s30, s30, s12
	s_addc_u32 s31, s31, 0
	s_mov_b32 m0, s49
	v_lshl_add_u64 v[204:205], s[30:31], 0, v[128:129]
	ds_read_b128 v[188:191], v145 offset:32768
	ds_read_b128 v[192:195], v145 offset:33792
	ds_read_b128 v[208:211], v145 offset:34816
	ds_read_b128 v[214:217], v145 offset:35840
	ds_read_b128 v[218:221], v145 offset:36864
	ds_read_b128 v[222:225], v145 offset:37888
	ds_read_b128 v[226:229], v145 offset:38912
	ds_read_b128 v[230:233], v145 offset:39936
	global_load_lds_dwordx4 v[204:205], off
	v_lshl_add_u64 v[204:205], s[30:31], 0, v[130:131]
	s_mov_b32 m0, s50
	s_nop 0
	global_load_lds_dwordx4 v[204:205], off
	s_waitcnt vmcnt(8)
	s_waitcnt lgkmcnt(0)
	s_barrier
	s_setprio 1
	s_waitcnt lgkmcnt(0)
	v_mfma_f32_16x16x32_bf16 v[124:127], v[138:141], v[188:191], v[124:127]
	v_mfma_f32_16x16x32_bf16 v[120:123], v[150:153], v[188:191], v[120:123]
	v_mfma_f32_16x16x32_bf16 v[108:111], v[138:141], v[208:211], v[108:111]
	v_mfma_f32_16x16x32_bf16 v[104:107], v[150:153], v[208:211], v[104:107]
	v_mfma_f32_16x16x32_bf16 v[92:95], v[138:141], v[218:221], v[92:95]
	v_mfma_f32_16x16x32_bf16 v[88:91], v[150:153], v[218:221], v[88:91]
	v_mfma_f32_16x16x32_bf16 v[76:79], v[138:141], v[226:229], v[76:79]
	v_mfma_f32_16x16x32_bf16 v[72:75], v[150:153], v[226:229], v[72:75]
	v_mfma_f32_16x16x32_bf16 v[124:127], v[146:149], v[192:195], v[124:127]
	v_mfma_f32_16x16x32_bf16 v[120:123], v[154:157], v[192:195], v[120:123]
	v_mfma_f32_16x16x32_bf16 v[108:111], v[146:149], v[214:217], v[108:111]
	v_mfma_f32_16x16x32_bf16 v[104:107], v[154:157], v[214:217], v[104:107]
	v_mfma_f32_16x16x32_bf16 v[92:95], v[146:149], v[222:225], v[92:95]
	v_mfma_f32_16x16x32_bf16 v[88:91], v[154:157], v[222:225], v[88:91]
	v_mfma_f32_16x16x32_bf16 v[76:79], v[146:149], v[230:233], v[76:79]
	v_mfma_f32_16x16x32_bf16 v[72:75], v[154:157], v[230:233], v[72:75]
	s_setprio 0
	s_setprio 1
	v_mfma_f32_16x16x32_bf16 v[116:119], v[162:165], v[188:191], v[116:119]
	v_mfma_f32_16x16x32_bf16 v[112:115], v[170:173], v[188:191], v[112:115]
	v_mfma_f32_16x16x32_bf16 v[100:103], v[162:165], v[208:211], v[100:103]
	v_mfma_f32_16x16x32_bf16 v[96:99], v[170:173], v[208:211], v[96:99]
	v_mfma_f32_16x16x32_bf16 v[84:87], v[162:165], v[218:221], v[84:87]
	v_mfma_f32_16x16x32_bf16 v[80:83], v[170:173], v[218:221], v[80:83]
	v_mfma_f32_16x16x32_bf16 v[68:71], v[162:165], v[226:229], v[68:71]
	v_mfma_f32_16x16x32_bf16 v[64:67], v[170:173], v[226:229], v[64:67]
	v_mfma_f32_16x16x32_bf16 v[116:119], v[166:169], v[192:195], v[116:119]
	v_mfma_f32_16x16x32_bf16 v[112:115], v[184:187], v[192:195], v[112:115]
	v_mfma_f32_16x16x32_bf16 v[100:103], v[166:169], v[214:217], v[100:103]
	v_mfma_f32_16x16x32_bf16 v[96:99], v[184:187], v[214:217], v[96:99]
	v_mfma_f32_16x16x32_bf16 v[84:87], v[166:169], v[222:225], v[84:87]
	v_mfma_f32_16x16x32_bf16 v[80:83], v[184:187], v[222:225], v[80:83]
	v_mfma_f32_16x16x32_bf16 v[68:71], v[166:169], v[230:233], v[68:71]
	v_mfma_f32_16x16x32_bf16 v[64:67], v[184:187], v[230:233], v[64:67]
	s_setprio 0
	s_barrier
; #define PG8_STAGE(bufoff, gbase, voff) do { _Pragma("unroll") for (int _i = 0; _i < 2; ++_i) \
;         __builtin_amdgcn_global_load_lds((const unsigned*)((const char*)(gbase) + (voff)[_i]), (PG8_LAS unsigned*)(lds + (bufoff) + ldsw + _i * 8192), 16, 0, 0); } while (0)
; #define PG8_LDA(dst, b, h) do { _Pragma("unroll") for (int m = 0; m < 4; ++m) _Pragma("unroll") for (int k = 0; k < 2; ++k) dst[m][k] = *(const PG8_LAS bf16x8*)(lds + PG8_SA(b, h) + aoff + m * 2048 + k * 1024); } while (0)
; #define PG8_MMA(ai, bj, At, Bt) do { __builtin_amdgcn_s_setprio(1); _Pragma("unroll") for (int m = 0; m < 4; ++m) _Pragma("unroll") for (int n = 0; n < 2; ++n) _Pragma("unroll") for (int k = 0; k < 2; ++k) \
;         acc[ai][bj][m][n] = __builtin_amdgcn_mfma_f32_16x16x32_bf16(Bt[n][k], At[m][k], acc[ai][bj][m][n], 0, 0, 0); __builtin_amdgcn_s_setprio(0); } while (0)
; #define PG8_WAIT_V(n) asm volatile("s_waitcnt vmcnt(" #n ")" ::: "memory")
; #define PG8_WAIT_L(n) asm volatile("s_waitcnt lgkmcnt(" #n ")" ::: "memory")
; #define PG8_BAR __builtin_amdgcn_s_barrier()
; #define PG8_SCHED __builtin_amdgcn_sched_barrier(0)
; template <class Epi, class Sched, bool ALIGN_EPI = false, bool SP2 = false>
; __device__ __forceinline__ void gemm_phase(PG8_LAS unsigned char* lds, const Gemm g, const Sched& S, const Epi& E, const int tid) {
;     ...
;             PG8_LDA(At, 1, 1); PG8_STAGE(PG8_SB(1, 0), b3, voffB); PG8_STAGE(PG8_SB(1, 1), b3 + hstep, voffB); PG8_STAGE(PG8_SA(1, 0), a3, voffA);
;             PG8_WAIT_V(8); PG8_WAIT_L(0); PG8_BAR; PG8_MMA(1, 0, At, B0); PG8_MMA(1, 1, At, B1); PG8_BAR; PG8_SCHED;
	s_add_i32 s30, s45, s46
	v_lshl_add_u64 v[158:159], v[158:159], 0, s[28:29]
	s_mov_b32 m0, s30
	ds_read_b128 v[188:191], v145 offset:49152
	ds_read_b128 v[192:195], v145 offset:50176
	ds_read_b128 v[208:211], v145 offset:51200
	ds_read_b128 v[214:217], v145 offset:52224
	ds_read_b128 v[218:221], v145 offset:53248
	ds_read_b128 v[222:225], v145 offset:54272
	ds_read_b128 v[226:229], v145 offset:55296
	ds_read_b128 v[230:233], v145 offset:56320
	global_load_lds_dwordx4 v[158:159], off
	v_lshl_add_u64 v[158:159], v[174:175], 0, s[28:29]
	s_add_i32 m0, s30, 0x2000
	s_add_i32 s30, s63, s46
	global_load_lds_dwordx4 v[158:159], off
	v_lshl_add_u64 v[158:159], v[178:179], 0, s[28:29]
	s_mov_b32 m0, s30
	s_nop 0
	global_load_lds_dwordx4 v[158:159], off
	v_lshl_add_u64 v[158:159], v[180:181], 0, s[28:29]
	s_add_i32 m0, s30, 0x2000
	s_nop 0
	global_load_lds_dwordx4 v[158:159], off
	v_lshl_add_u64 v[158:159], v[196:197], 0, s[28:29]
	s_mov_b32 m0, s51
	s_nop 0
	global_load_lds_dwordx4 v[158:159], off
	v_lshl_add_u64 v[158:159], v[198:199], 0, s[28:29]
	s_mov_b32 m0, s52
	s_nop 0
	global_load_lds_dwordx4 v[158:159], off
	s_waitcnt vmcnt(8)
	s_waitcnt lgkmcnt(0)
	s_barrier
	s_setprio 1
	s_waitcnt lgkmcnt(0)
	v_mfma_f32_16x16x32_bf16 v[60:63], v[138:141], v[188:191], v[60:63]
	v_mfma_f32_16x16x32_bf16 v[56:59], v[150:153], v[188:191], v[56:59]
	v_mfma_f32_16x16x32_bf16 v[44:47], v[138:141], v[208:211], v[44:47]
	v_mfma_f32_16x16x32_bf16 v[40:43], v[150:153], v[208:211], v[40:43]
	v_mfma_f32_16x16x32_bf16 v[28:31], v[138:141], v[218:221], v[28:31]
	v_mfma_f32_16x16x32_bf16 v[24:27], v[150:153], v[218:221], v[24:27]
	v_mfma_f32_16x16x32_bf16 v[12:15], v[138:141], v[226:229], v[12:15]
	v_mfma_f32_16x16x32_bf16 v[8:11], v[150:153], v[226:229], v[8:11]
	v_mfma_f32_16x16x32_bf16 v[60:63], v[146:149], v[192:195], v[60:63]
	v_mfma_f32_16x16x32_bf16 v[56:59], v[154:157], v[192:195], v[56:59]
	v_mfma_f32_16x16x32_bf16 v[44:47], v[146:149], v[214:217], v[44:47]
	v_mfma_f32_16x16x32_bf16 v[40:43], v[154:157], v[214:217], v[40:43]
	v_mfma_f32_16x16x32_bf16 v[28:31], v[146:149], v[222:225], v[28:31]
	v_mfma_f32_16x16x32_bf16 v[24:27], v[154:157], v[222:225], v[24:27]
	v_mfma_f32_16x16x32_bf16 v[12:15], v[146:149], v[230:233], v[12:15]
	v_mfma_f32_16x16x32_bf16 v[8:11], v[154:157], v[230:233], v[8:11]
	s_setprio 0
	s_setprio 1
	v_mfma_f32_16x16x32_bf16 v[52:55], v[162:165], v[188:191], v[52:55]
	v_mfma_f32_16x16x32_bf16 v[48:51], v[170:173], v[188:191], v[48:51]
	v_mfma_f32_16x16x32_bf16 v[36:39], v[162:165], v[208:211], v[36:39]
	v_mfma_f32_16x16x32_bf16 v[32:35], v[170:173], v[208:211], v[32:35]
	v_mfma_f32_16x16x32_bf16 v[20:23], v[162:165], v[218:221], v[20:23]
	v_mfma_f32_16x16x32_bf16 v[16:19], v[170:173], v[218:221], v[16:19]
	v_mfma_f32_16x16x32_bf16 v[4:7], v[162:165], v[226:229], v[4:7]
	v_mfma_f32_16x16x32_bf16 v[0:3], v[170:173], v[226:229], v[0:3]
	v_mfma_f32_16x16x32_bf16 v[52:55], v[166:169], v[192:195], v[52:55]
	v_mfma_f32_16x16x32_bf16 v[48:51], v[184:187], v[192:195], v[48:51]
	v_mfma_f32_16x16x32_bf16 v[36:39], v[166:169], v[214:217], v[36:39]
	v_mfma_f32_16x16x32_bf16 v[32:35], v[184:187], v[214:217], v[32:35]
	v_mfma_f32_16x16x32_bf16 v[20:23], v[166:169], v[222:225], v[20:23]
	v_mfma_f32_16x16x32_bf16 v[16:19], v[184:187], v[222:225], v[16:19]
	v_mfma_f32_16x16x32_bf16 v[4:7], v[166:169], v[230:233], v[4:7]
	v_mfma_f32_16x16x32_bf16 v[0:3], v[184:187], v[230:233], v[0:3]
	s_setprio 0
	s_barrier
	s_add_u32 s26, s26, 0x100
	s_addc_u32 s27, s27, 0
	s_add_u32 s36, s36, 0x100
	s_addc_u32 s37, s37, 0
	s_cmp_ge_u32 s44, s57
	s_mov_b32 s30, s44
	s_cbranch_scc1 .Lmy_kdone_0
	.p2align	6

; #define PG8_STAGE(bufoff, gbase, voff) do { _Pragma("unroll") for (int _i = 0; _i < 2; ++_i) \
;         __builtin_amdgcn_global_load_lds((const unsigned*)((const char*)(gbase) + (voff)[_i]), (PG8_LAS unsigned*)(lds + (bufoff) + ldsw + _i * 8192), 16, 0, 0); } while (0)
; #define PG8_LDA(dst, b, h) do { _Pragma("unroll") for (int m = 0; m < 4; ++m) _Pragma("unroll") for (int k = 0; k < 2; ++k) dst[m][k] = *(const PG8_LAS bf16x8*)(lds + PG8_SA(b, h) + aoff + m * 2048 + k * 1024); } while (0)
; #define PG8_LDB(dst, b, h) do { _Pragma("unroll") for (int n = 0; n < 2; ++n) _Pragma("unroll") for (int k = 0; k < 2; ++k) dst[n][k] = *(const PG8_LAS bf16x8*)(lds + PG8_SB(b, h) + boff + n * 2048 + k * 1024); } while (0)
; #define PG8_MMA(ai, bj, At, Bt) do { __builtin_amdgcn_s_setprio(1); _Pragma("unroll") for (int m = 0; m < 4; ++m) _Pragma("unroll") for (int n = 0; n < 2; ++n) _Pragma("unroll") for (int k = 0; k < 2; ++k) \
;         acc[ai][bj][m][n] = __builtin_amdgcn_mfma_f32_16x16x32_bf16(Bt[n][k], At[m][k], acc[ai][bj][m][n], 0, 0, 0); __builtin_amdgcn_s_setprio(0); } while (0)
; #define PG8_WAIT_V(n) asm volatile("s_waitcnt vmcnt(" #n ")" ::: "memory")
; #define PG8_WAIT_L(n) asm volatile("s_waitcnt lgkmcnt(" #n ")" ::: "memory")
; #define PG8_BAR __builtin_amdgcn_s_barrier()
; #define PG8_SCHED __builtin_amdgcn_sched_barrier(0)
; template <class Epi, class Sched, bool ALIGN_EPI = false, bool SP2 = false>
; __device__ __forceinline__ void gemm_phase(PG8_LAS unsigned char* lds, const Gemm g, const Sched& S, const Epi& E, const int tid) {
;     ...
;             PG8_WAIT_V(8); PG8_WAIT_L(0); PG8_BAR; PG8_MMA(1, 0, At, B0); PG8_MMA(1, 1, At, B1); PG8_BAR; PG8_SCHED;
;             PG8_LDB(B0, 1, 0); PG8_LDB(B1, 1, 1); PG8_SCHED; PG8_LDA(At, 1, 0); PG8_STAGE(PG8_SA(0, 1), a2 + hstep, voffA);
;             PG8_WAIT_V(8); PG8_WAIT_L(0); PG8_BAR; PG8_MMA(0, 0, At, B0); PG8_MMA(0, 1, At, B1); PG8_BAR; PG8_SCHED;
.Lmy_wj_1:
	s_waitcnt lgkmcnt(0)
	s_barrier
	s_setprio 1
	s_waitcnt lgkmcnt(0)
	v_mfma_f32_16x16x32_bf16 v[60:63], v[140:143], v[208:211], 0
	v_mfma_f32_16x16x32_bf16 v[56:59], v[162:165], v[208:211], 0
	v_mfma_f32_16x16x32_bf16 v[44:47], v[140:143], v[218:221], 0
	v_mfma_f32_16x16x32_bf16 v[40:43], v[162:165], v[218:221], 0
	v_mfma_f32_16x16x32_bf16 v[28:31], v[140:143], v[226:229], 0
	v_mfma_f32_16x16x32_bf16 v[24:27], v[162:165], v[226:229], 0
	v_mfma_f32_16x16x32_bf16 v[12:15], v[140:143], v[234:237], 0
	v_mfma_f32_16x16x32_bf16 v[8:11], v[162:165], v[234:237], 0
	v_mfma_f32_16x16x32_bf16 v[60:63], v[154:157], v[214:217], v[60:63]
	v_mfma_f32_16x16x32_bf16 v[56:59], v[166:169], v[214:217], v[56:59]
	v_mfma_f32_16x16x32_bf16 v[44:47], v[154:157], v[222:225], v[44:47]
	v_mfma_f32_16x16x32_bf16 v[40:43], v[166:169], v[222:225], v[40:43]
	v_mfma_f32_16x16x32_bf16 v[28:31], v[154:157], v[230:233], v[28:31]
	v_mfma_f32_16x16x32_bf16 v[24:27], v[166:169], v[230:233], v[24:27]
	v_mfma_f32_16x16x32_bf16 v[12:15], v[154:157], v[238:241], v[12:15]
	v_mfma_f32_16x16x32_bf16 v[8:11], v[166:169], v[238:241], v[8:11]
	s_setprio 0
	s_setprio 1
	v_mfma_f32_16x16x32_bf16 v[52:55], v[170:173], v[208:211], 0
	v_mfma_f32_16x16x32_bf16 v[48:51], v[188:191], v[208:211], 0
	v_mfma_f32_16x16x32_bf16 v[36:39], v[170:173], v[218:221], 0
	v_mfma_f32_16x16x32_bf16 v[32:35], v[188:191], v[218:221], 0
	v_mfma_f32_16x16x32_bf16 v[20:23], v[170:173], v[226:229], 0
	v_mfma_f32_16x16x32_bf16 v[16:19], v[188:191], v[226:229], 0
	v_mfma_f32_16x16x32_bf16 v[4:7], v[170:173], v[234:237], 0
	v_mfma_f32_16x16x32_bf16 v[0:3], v[188:191], v[234:237], 0
	v_mfma_f32_16x16x32_bf16 v[52:55], v[184:187], v[214:217], v[52:55]
	v_mfma_f32_16x16x32_bf16 v[48:51], v[192:195], v[214:217], v[48:51]
	v_mfma_f32_16x16x32_bf16 v[36:39], v[184:187], v[222:225], v[36:39]
	v_mfma_f32_16x16x32_bf16 v[32:35], v[192:195], v[222:225], v[32:35]
	v_mfma_f32_16x16x32_bf16 v[20:23], v[184:187], v[230:233], v[20:23]
	v_mfma_f32_16x16x32_bf16 v[16:19], v[192:195], v[230:233], v[16:19]
	v_mfma_f32_16x16x32_bf16 v[4:7], v[184:187], v[238:241], v[4:7]
	v_mfma_f32_16x16x32_bf16 v[0:3], v[192:195], v[238:241], v[0:3]
	s_setprio 0
	s_barrier
	s_add_i32 s56, 0, 0x18000
	v_add_u32_e32 v138, s56, v147
	s_add_i32 s57, 0, 0x1c000
	ds_read_b128 v[140:143], v138
	ds_read_b128 v[154:157], v138 offset:1024
	ds_read_b128 v[162:165], v138 offset:2048
	ds_read_b128 v[166:169], v138 offset:3072
	v_add_u32_e32 v138, s57, v147
	ds_read_b128 v[170:173], v138
	ds_read_b128 v[184:187], v138 offset:1024
	ds_read_b128 v[188:191], v138 offset:2048
	ds_read_b128 v[192:195], v138 offset:3072
	s_add_u32 s20, s20, 0x40000
	s_addc_u32 s21, s21, 0
	s_mov_b32 m0, s31
	v_lshl_add_u64 v[196:197], s[20:21], 0, v[128:129]
	ds_read_b128 v[208:211], v153 offset:32768
	ds_read_b128 v[214:217], v153 offset:33792
	ds_read_b128 v[218:221], v153 offset:34816
	ds_read_b128 v[222:225], v153 offset:35840
	ds_read_b128 v[226:229], v153 offset:36864
	ds_read_b128 v[230:233], v153 offset:37888
	ds_read_b128 v[234:237], v153 offset:38912
	ds_read_b128 v[238:241], v153 offset:39936
	global_load_lds_dwordx4 v[196:197], off
	v_lshl_add_u64 v[196:197], s[20:21], 0, v[130:131]
	s_mov_b32 m0, s34
	s_nop 0
	global_load_lds_dwordx4 v[196:197], off
	s_waitcnt vmcnt(8)
	s_waitcnt lgkmcnt(0)
	s_barrier
	s_setprio 1
	s_waitcnt lgkmcnt(0)
	v_mfma_f32_16x16x32_bf16 v[124:127], v[140:143], v[208:211], v[124:127]
	v_mfma_f32_16x16x32_bf16 v[120:123], v[162:165], v[208:211], v[120:123]
	v_mfma_f32_16x16x32_bf16 v[108:111], v[140:143], v[218:221], v[108:111]
	v_mfma_f32_16x16x32_bf16 v[104:107], v[162:165], v[218:221], v[104:107]
	v_mfma_f32_16x16x32_bf16 v[92:95], v[140:143], v[226:229], v[92:95]
	v_mfma_f32_16x16x32_bf16 v[88:91], v[162:165], v[226:229], v[88:91]
	v_mfma_f32_16x16x32_bf16 v[76:79], v[140:143], v[234:237], v[76:79]
	v_mfma_f32_16x16x32_bf16 v[72:75], v[162:165], v[234:237], v[72:75]
	v_mfma_f32_16x16x32_bf16 v[124:127], v[154:157], v[214:217], v[124:127]
	v_mfma_f32_16x16x32_bf16 v[120:123], v[166:169], v[214:217], v[120:123]
	v_mfma_f32_16x16x32_bf16 v[108:111], v[154:157], v[222:225], v[108:111]
	v_mfma_f32_16x16x32_bf16 v[104:107], v[166:169], v[222:225], v[104:107]
	v_mfma_f32_16x16x32_bf16 v[92:95], v[154:157], v[230:233], v[92:95]
	v_mfma_f32_16x16x32_bf16 v[88:91], v[166:169], v[230:233], v[88:91]
	v_mfma_f32_16x16x32_bf16 v[76:79], v[154:157], v[238:241], v[76:79]
	v_mfma_f32_16x16x32_bf16 v[72:75], v[166:169], v[238:241], v[72:75]
	s_setprio 0
	s_setprio 1
	v_mfma_f32_16x16x32_bf16 v[116:119], v[170:173], v[208:211], v[116:119]
	v_mfma_f32_16x16x32_bf16 v[112:115], v[188:191], v[208:211], v[112:115]
	v_mfma_f32_16x16x32_bf16 v[100:103], v[170:173], v[218:221], v[100:103]
	v_mfma_f32_16x16x32_bf16 v[96:99], v[188:191], v[218:221], v[96:99]
	v_mfma_f32_16x16x32_bf16 v[84:87], v[170:173], v[226:229], v[84:87]
	v_mfma_f32_16x16x32_bf16 v[80:83], v[188:191], v[226:229], v[80:83]
	v_mfma_f32_16x16x32_bf16 v[68:71], v[170:173], v[234:237], v[68:71]
	v_mfma_f32_16x16x32_bf16 v[64:67], v[188:191], v[234:237], v[64:67]
	v_mfma_f32_16x16x32_bf16 v[116:119], v[184:187], v[214:217], v[116:119]
	v_mfma_f32_16x16x32_bf16 v[112:115], v[192:195], v[214:217], v[112:115]
	v_mfma_f32_16x16x32_bf16 v[100:103], v[184:187], v[222:225], v[100:103]
	v_mfma_f32_16x16x32_bf16 v[96:99], v[192:195], v[222:225], v[96:99]
	v_mfma_f32_16x16x32_bf16 v[84:87], v[184:187], v[230:233], v[84:87]
	v_mfma_f32_16x16x32_bf16 v[80:83], v[192:195], v[230:233], v[80:83]
	v_mfma_f32_16x16x32_bf16 v[68:71], v[184:187], v[238:241], v[68:71]
	v_mfma_f32_16x16x32_bf16 v[64:67], v[192:195], v[238:241], v[64:67]
	s_setprio 0
	s_barrier
; #define PG8_STAGE(bufoff, gbase, voff) do { _Pragma("unroll") for (int _i = 0; _i < 2; ++_i) \
;         __builtin_amdgcn_global_load_lds((const unsigned*)((const char*)(gbase) + (voff)[_i]), (PG8_LAS unsigned*)(lds + (bufoff) + ldsw + _i * 8192), 16, 0, 0); } while (0)
; #define PG8_LDA(dst, b, h) do { _Pragma("unroll") for (int m = 0; m < 4; ++m) _Pragma("unroll") for (int k = 0; k < 2; ++k) dst[m][k] = *(const PG8_LAS bf16x8*)(lds + PG8_SA(b, h) + aoff + m * 2048 + k * 1024); } while (0)
; #define PG8_MMA(ai, bj, At, Bt) do { __builtin_amdgcn_s_setprio(1); _Pragma("unroll") for (int m = 0; m < 4; ++m) _Pragma("unroll") for (int n = 0; n < 2; ++n) _Pragma("unroll") for (int k = 0; k < 2; ++k) \
;         acc[ai][bj][m][n] = __builtin_amdgcn_mfma_f32_16x16x32_bf16(Bt[n][k], At[m][k], acc[ai][bj][m][n], 0, 0, 0); __builtin_amdgcn_s_setprio(0); } while (0)
; #define PG8_WAIT_V(n) asm volatile("s_waitcnt vmcnt(" #n ")" ::: "memory")
; #define PG8_WAIT_L(n) asm volatile("s_waitcnt lgkmcnt(" #n ")" ::: "memory")
; #define PG8_BAR __builtin_amdgcn_s_barrier()
; #define PG8_SCHED __builtin_amdgcn_sched_barrier(0)
; template <class Epi, class Sched, bool ALIGN_EPI = false, bool SP2 = false>
; __device__ __forceinline__ void gemm_phase(PG8_LAS unsigned char* lds, const Gemm g, const Sched& S, const Epi& E, const int tid) {
;     ...
;             PG8_LDA(At, 1, 1); PG8_STAGE(PG8_SB(1, 0), b3, voffB); PG8_STAGE(PG8_SB(1, 1), b3 + hstep, voffB); PG8_STAGE(PG8_SA(1, 0), a3, voffA);
;             PG8_WAIT_V(8); PG8_WAIT_L(0); PG8_BAR; PG8_MMA(1, 0, At, B0); PG8_MMA(1, 1, At, B1); PG8_BAR; PG8_SCHED;
	s_add_i32 s20, s56, s27
	v_lshl_add_u64 v[158:159], v[158:159], 0, s[28:29]
	s_mov_b32 m0, s20
	ds_read_b128 v[208:211], v153 offset:49152
	ds_read_b128 v[214:217], v153 offset:50176
	ds_read_b128 v[218:221], v153 offset:51200
	ds_read_b128 v[222:225], v153 offset:52224
	ds_read_b128 v[226:229], v153 offset:53248
	ds_read_b128 v[230:233], v153 offset:54272
	ds_read_b128 v[234:237], v153 offset:55296
	ds_read_b128 v[238:241], v153 offset:56320
	global_load_lds_dwordx4 v[158:159], off
	s_add_i32 m0, s20, 0x2000
	s_add_u32 s16, s16, 0x40080
	v_lshl_add_u64 v[158:159], v[174:175], 0, s[28:29]
	s_addc_u32 s17, s17, 0
	s_add_i32 s20, s57, s27
	global_load_lds_dwordx4 v[158:159], off
	v_lshl_add_u64 v[158:159], s[16:17], 0, v[160:161]
	s_mov_b32 m0, s20
	s_nop 0
	global_load_lds_dwordx4 v[158:159], off
	v_lshl_add_u64 v[158:159], s[16:17], 0, v[132:133]
	s_add_i32 m0, s20, 0x2000
	s_nop 0
	global_load_lds_dwordx4 v[158:159], off
	v_lshl_add_u64 v[158:159], v[178:179], 0, s[28:29]
	s_mov_b32 m0, s81
	s_nop 0
	global_load_lds_dwordx4 v[158:159], off
	v_lshl_add_u64 v[158:159], v[180:181], 0, s[28:29]
	s_mov_b32 m0, s82
	s_nop 0
	global_load_lds_dwordx4 v[158:159], off
	s_waitcnt vmcnt(8)
	s_waitcnt lgkmcnt(0)
	s_barrier
	s_setprio 1
	s_waitcnt lgkmcnt(0)
	v_mfma_f32_16x16x32_bf16 v[60:63], v[140:143], v[208:211], v[60:63]
	v_mfma_f32_16x16x32_bf16 v[56:59], v[162:165], v[208:211], v[56:59]
	v_mfma_f32_16x16x32_bf16 v[44:47], v[140:143], v[218:221], v[44:47]
	v_mfma_f32_16x16x32_bf16 v[40:43], v[162:165], v[218:221], v[40:43]
	v_mfma_f32_16x16x32_bf16 v[28:31], v[140:143], v[226:229], v[28:31]
	v_mfma_f32_16x16x32_bf16 v[24:27], v[162:165], v[226:229], v[24:27]
	v_mfma_f32_16x16x32_bf16 v[12:15], v[140:143], v[234:237], v[12:15]
	v_mfma_f32_16x16x32_bf16 v[8:11], v[162:165], v[234:237], v[8:11]
	v_mfma_f32_16x16x32_bf16 v[60:63], v[154:157], v[214:217], v[60:63]
	v_mfma_f32_16x16x32_bf16 v[56:59], v[166:169], v[214:217], v[56:59]
	v_mfma_f32_16x16x32_bf16 v[44:47], v[154:157], v[222:225], v[44:47]
	v_mfma_f32_16x16x32_bf16 v[40:43], v[166:169], v[222:225], v[40:43]
	v_mfma_f32_16x16x32_bf16 v[28:31], v[154:157], v[230:233], v[28:31]
	v_mfma_f32_16x16x32_bf16 v[24:27], v[166:169], v[230:233], v[24:27]
	v_mfma_f32_16x16x32_bf16 v[12:15], v[154:157], v[238:241], v[12:15]
	v_mfma_f32_16x16x32_bf16 v[8:11], v[166:169], v[238:241], v[8:11]
	s_setprio 0
	s_setprio 1
	v_mfma_f32_16x16x32_bf16 v[52:55], v[170:173], v[208:211], v[52:55]
	v_mfma_f32_16x16x32_bf16 v[48:51], v[188:191], v[208:211], v[48:51]
	v_mfma_f32_16x16x32_bf16 v[36:39], v[170:173], v[218:221], v[36:39]
	v_mfma_f32_16x16x32_bf16 v[32:35], v[188:191], v[218:221], v[32:35]
	v_mfma_f32_16x16x32_bf16 v[20:23], v[170:173], v[226:229], v[20:23]
	v_mfma_f32_16x16x32_bf16 v[16:19], v[188:191], v[226:229], v[16:19]
	v_mfma_f32_16x16x32_bf16 v[4:7], v[170:173], v[234:237], v[4:7]
	v_mfma_f32_16x16x32_bf16 v[0:3], v[188:191], v[234:237], v[0:3]
	v_mfma_f32_16x16x32_bf16 v[52:55], v[184:187], v[214:217], v[52:55]
	v_mfma_f32_16x16x32_bf16 v[48:51], v[192:195], v[214:217], v[48:51]
	v_mfma_f32_16x16x32_bf16 v[36:39], v[184:187], v[222:225], v[36:39]
	v_mfma_f32_16x16x32_bf16 v[32:35], v[192:195], v[222:225], v[32:35]
	v_mfma_f32_16x16x32_bf16 v[20:23], v[184:187], v[230:233], v[20:23]
	v_mfma_f32_16x16x32_bf16 v[16:19], v[192:195], v[230:233], v[16:19]
	v_mfma_f32_16x16x32_bf16 v[4:7], v[184:187], v[238:241], v[4:7]
	v_mfma_f32_16x16x32_bf16 v[0:3], v[192:195], v[238:241], v[0:3]
	s_setprio 0
	s_barrier
	s_add_i32 s51, s51, 2
	s_add_u32 s14, s14, 0x100
	s_addc_u32 s15, s15, 0
	s_add_u32 s43, s43, 0x100
	s_addc_u32 s49, s49, 0
	s_cmp_gt_u32 s51, 13
	s_cbranch_scc1 .Lmy_kdone_1
	.p2align	6

; #define PG8_STAGE(bufoff, gbase, voff) do { _Pragma("unroll") for (int _i = 0; _i < 2; ++_i) \
;         __builtin_amdgcn_global_load_lds((const unsigned*)((const char*)(gbase) + (voff)[_i]), (PG8_LAS unsigned*)(lds + (bufoff) + ldsw + _i * 8192), 16, 0, 0); } while (0)
; #define PG8_LDA(dst, b, h) do { _Pragma("unroll") for (int m = 0; m < 4; ++m) _Pragma("unroll") for (int k = 0; k < 2; ++k) dst[m][k] = *(const PG8_LAS bf16x8*)(lds + PG8_SA(b, h) + aoff + m * 2048 + k * 1024); } while (0)
; #define PG8_LDB(dst, b, h) do { _Pragma("unroll") for (int n = 0; n < 2; ++n) _Pragma("unroll") for (int k = 0; k < 2; ++k) dst[n][k] = *(const PG8_LAS bf16x8*)(lds + PG8_SB(b, h) + boff + n * 2048 + k * 1024); } while (0)
; #define PG8_MMA(ai, bj, At, Bt) do { __builtin_amdgcn_s_setprio(1); _Pragma("unroll") for (int m = 0; m < 4; ++m) _Pragma("unroll") for (int n = 0; n < 2; ++n) _Pragma("unroll") for (int k = 0; k < 2; ++k) \
;         acc[ai][bj][m][n] = __builtin_amdgcn_mfma_f32_16x16x32_bf16(Bt[n][k], At[m][k], acc[ai][bj][m][n], 0, 0, 0); __builtin_amdgcn_s_setprio(0); } while (0)
; #define PG8_WAIT_V(n) asm volatile("s_waitcnt vmcnt(" #n ")" ::: "memory")
; #define PG8_WAIT_L(n) asm volatile("s_waitcnt lgkmcnt(" #n ")" ::: "memory")
; #define PG8_BAR __builtin_amdgcn_s_barrier()
; #define PG8_SCHED __builtin_amdgcn_sched_barrier(0)
; template <class Epi, class Sched, bool ALIGN_EPI = false, bool SP2 = false>
; __device__ __forceinline__ void gemm_phase(PG8_LAS unsigned char* lds, const Gemm g, const Sched& S, const Epi& E, const int tid) {
;     ...
;             PG8_WAIT_V(8); PG8_WAIT_L(0); PG8_BAR; PG8_MMA(1, 0, At, B0); PG8_MMA(1, 1, At, B1); PG8_BAR; PG8_SCHED;
;             PG8_LDB(B0, 1, 0); PG8_LDB(B1, 1, 1); PG8_SCHED; PG8_LDA(At, 1, 0); PG8_STAGE(PG8_SA(0, 1), a2 + hstep, voffA);
;             PG8_WAIT_V(8); PG8_WAIT_L(0); PG8_BAR; PG8_MMA(0, 0, At, B0); PG8_MMA(0, 1, At, B1); PG8_BAR; PG8_SCHED;
.Lmy_wj_2:
	s_waitcnt lgkmcnt(0)
	s_barrier
	s_setprio 1
	s_waitcnt lgkmcnt(0)
	v_mfma_f32_16x16x32_bf16 v[60:63], v[150:153], v[208:211], 0
	v_mfma_f32_16x16x32_bf16 v[52:55], v[162:165], v[208:211], 0
	v_mfma_f32_16x16x32_bf16 v[44:47], v[150:153], v[218:221], 0
	v_mfma_f32_16x16x32_bf16 v[36:39], v[162:165], v[218:221], 0
	v_mfma_f32_16x16x32_bf16 v[28:31], v[150:153], v[226:229], 0
	v_mfma_f32_16x16x32_bf16 v[20:23], v[162:165], v[226:229], 0
	v_mfma_f32_16x16x32_bf16 v[12:15], v[150:153], v[234:237], 0
	v_mfma_f32_16x16x32_bf16 v[4:7], v[162:165], v[234:237], 0
	v_mfma_f32_16x16x32_bf16 v[60:63], v[154:157], v[214:217], v[60:63]
	v_mfma_f32_16x16x32_bf16 v[52:55], v[166:169], v[214:217], v[52:55]
	v_mfma_f32_16x16x32_bf16 v[44:47], v[154:157], v[222:225], v[44:47]
	v_mfma_f32_16x16x32_bf16 v[36:39], v[166:169], v[222:225], v[36:39]
	v_mfma_f32_16x16x32_bf16 v[28:31], v[154:157], v[230:233], v[28:31]
	v_mfma_f32_16x16x32_bf16 v[20:23], v[166:169], v[230:233], v[20:23]
	v_mfma_f32_16x16x32_bf16 v[12:15], v[154:157], v[238:241], v[12:15]
	v_mfma_f32_16x16x32_bf16 v[4:7], v[166:169], v[238:241], v[4:7]
	s_setprio 0
	s_setprio 1
	v_mfma_f32_16x16x32_bf16 v[56:59], v[170:173], v[208:211], 0
	v_mfma_f32_16x16x32_bf16 v[48:51], v[188:191], v[208:211], 0
	v_mfma_f32_16x16x32_bf16 v[40:43], v[170:173], v[218:221], 0
	v_mfma_f32_16x16x32_bf16 v[32:35], v[188:191], v[218:221], 0
	v_mfma_f32_16x16x32_bf16 v[24:27], v[170:173], v[226:229], 0
	v_mfma_f32_16x16x32_bf16 v[16:19], v[188:191], v[226:229], 0
	v_mfma_f32_16x16x32_bf16 v[8:11], v[170:173], v[234:237], 0
	v_mfma_f32_16x16x32_bf16 v[0:3], v[188:191], v[234:237], 0
	v_mfma_f32_16x16x32_bf16 v[56:59], v[184:187], v[214:217], v[56:59]
	v_mfma_f32_16x16x32_bf16 v[48:51], v[192:195], v[214:217], v[48:51]
	v_mfma_f32_16x16x32_bf16 v[40:43], v[184:187], v[222:225], v[40:43]
	v_mfma_f32_16x16x32_bf16 v[32:35], v[192:195], v[222:225], v[32:35]
	v_mfma_f32_16x16x32_bf16 v[24:27], v[184:187], v[230:233], v[24:27]
	v_mfma_f32_16x16x32_bf16 v[16:19], v[192:195], v[230:233], v[16:19]
	v_mfma_f32_16x16x32_bf16 v[8:11], v[184:187], v[238:241], v[8:11]
	v_mfma_f32_16x16x32_bf16 v[0:3], v[192:195], v[238:241], v[0:3]
	s_setprio 0
	s_barrier
	s_add_i32 s52, 0, 0x18000
	v_add_u32_e32 v138, s52, v141
	s_add_i32 s53, 0, 0x1c000
	ds_read_b128 v[150:153], v138
	ds_read_b128 v[154:157], v138 offset:1024
	ds_read_b128 v[162:165], v138 offset:2048
	ds_read_b128 v[166:169], v138 offset:3072
	v_add_u32_e32 v138, s53, v141
	ds_read_b128 v[170:173], v138
	ds_read_b128 v[184:187], v138 offset:1024
	ds_read_b128 v[188:191], v138 offset:2048
	ds_read_b128 v[192:195], v138 offset:3072
	s_add_u32 s22, s22, 0x40000
	s_addc_u32 s23, s23, 0
	s_mov_b32 m0, s45
	v_lshl_add_u64 v[196:197], s[22:23], 0, v[128:129]
	ds_read_b128 v[208:211], v149 offset:32768
	ds_read_b128 v[214:217], v149 offset:33792
	ds_read_b128 v[218:221], v149 offset:34816
	ds_read_b128 v[222:225], v149 offset:35840
	ds_read_b128 v[226:229], v149 offset:36864
	ds_read_b128 v[230:233], v149 offset:37888
	ds_read_b128 v[234:237], v149 offset:38912
	ds_read_b128 v[238:241], v149 offset:39936
	global_load_lds_dwordx4 v[196:197], off
	v_lshl_add_u64 v[196:197], s[22:23], 0, v[130:131]
	s_mov_b32 m0, s46
	s_nop 0
	global_load_lds_dwordx4 v[196:197], off
	s_waitcnt vmcnt(8)
	s_waitcnt lgkmcnt(0)
	s_barrier
	s_setprio 1
	s_waitcnt lgkmcnt(0)
	v_mfma_f32_16x16x32_bf16 v[124:127], v[150:153], v[208:211], v[124:127]
	v_mfma_f32_16x16x32_bf16 v[116:119], v[162:165], v[208:211], v[116:119]
	v_mfma_f32_16x16x32_bf16 v[108:111], v[150:153], v[218:221], v[108:111]
	v_mfma_f32_16x16x32_bf16 v[100:103], v[162:165], v[218:221], v[100:103]
	v_mfma_f32_16x16x32_bf16 v[92:95], v[150:153], v[226:229], v[92:95]
	v_mfma_f32_16x16x32_bf16 v[84:87], v[162:165], v[226:229], v[84:87]
	v_mfma_f32_16x16x32_bf16 v[76:79], v[150:153], v[234:237], v[76:79]
	v_mfma_f32_16x16x32_bf16 v[68:71], v[162:165], v[234:237], v[68:71]
	v_mfma_f32_16x16x32_bf16 v[124:127], v[154:157], v[214:217], v[124:127]
	v_mfma_f32_16x16x32_bf16 v[116:119], v[166:169], v[214:217], v[116:119]
	v_mfma_f32_16x16x32_bf16 v[108:111], v[154:157], v[222:225], v[108:111]
	v_mfma_f32_16x16x32_bf16 v[100:103], v[166:169], v[222:225], v[100:103]
	v_mfma_f32_16x16x32_bf16 v[92:95], v[154:157], v[230:233], v[92:95]
	v_mfma_f32_16x16x32_bf16 v[84:87], v[166:169], v[230:233], v[84:87]
	v_mfma_f32_16x16x32_bf16 v[76:79], v[154:157], v[238:241], v[76:79]
	v_mfma_f32_16x16x32_bf16 v[68:71], v[166:169], v[238:241], v[68:71]
	s_setprio 0
	s_setprio 1
	v_mfma_f32_16x16x32_bf16 v[120:123], v[170:173], v[208:211], v[120:123]
	v_mfma_f32_16x16x32_bf16 v[112:115], v[188:191], v[208:211], v[112:115]
	v_mfma_f32_16x16x32_bf16 v[104:107], v[170:173], v[218:221], v[104:107]
	v_mfma_f32_16x16x32_bf16 v[96:99], v[188:191], v[218:221], v[96:99]
	v_mfma_f32_16x16x32_bf16 v[88:91], v[170:173], v[226:229], v[88:91]
	v_mfma_f32_16x16x32_bf16 v[80:83], v[188:191], v[226:229], v[80:83]
	v_mfma_f32_16x16x32_bf16 v[72:75], v[170:173], v[234:237], v[72:75]
	v_mfma_f32_16x16x32_bf16 v[64:67], v[188:191], v[234:237], v[64:67]
	v_mfma_f32_16x16x32_bf16 v[120:123], v[184:187], v[214:217], v[120:123]
	v_mfma_f32_16x16x32_bf16 v[112:115], v[192:195], v[214:217], v[112:115]
	v_mfma_f32_16x16x32_bf16 v[104:107], v[184:187], v[222:225], v[104:107]
	v_mfma_f32_16x16x32_bf16 v[96:99], v[192:195], v[222:225], v[96:99]
	v_mfma_f32_16x16x32_bf16 v[88:91], v[184:187], v[230:233], v[88:91]
	v_mfma_f32_16x16x32_bf16 v[80:83], v[192:195], v[230:233], v[80:83]
	v_mfma_f32_16x16x32_bf16 v[72:75], v[184:187], v[238:241], v[72:75]
	v_mfma_f32_16x16x32_bf16 v[64:67], v[192:195], v[238:241], v[64:67]
	s_setprio 0
	s_barrier
; #define PG8_STAGE(bufoff, gbase, voff) do { _Pragma("unroll") for (int _i = 0; _i < 2; ++_i) \
;         __builtin_amdgcn_global_load_lds((const unsigned*)((const char*)(gbase) + (voff)[_i]), (PG8_LAS unsigned*)(lds + (bufoff) + ldsw + _i * 8192), 16, 0, 0); } while (0)
; #define PG8_LDA(dst, b, h) do { _Pragma("unroll") for (int m = 0; m < 4; ++m) _Pragma("unroll") for (int k = 0; k < 2; ++k) dst[m][k] = *(const PG8_LAS bf16x8*)(lds + PG8_SA(b, h) + aoff + m * 2048 + k * 1024); } while (0)
; #define PG8_MMA(ai, bj, At, Bt) do { __builtin_amdgcn_s_setprio(1); _Pragma("unroll") for (int m = 0; m < 4; ++m) _Pragma("unroll") for (int n = 0; n < 2; ++n) _Pragma("unroll") for (int k = 0; k < 2; ++k) \
;         acc[ai][bj][m][n] = __builtin_amdgcn_mfma_f32_16x16x32_bf16(Bt[n][k], At[m][k], acc[ai][bj][m][n], 0, 0, 0); __builtin_amdgcn_s_setprio(0); } while (0)
; #define PG8_WAIT_V(n) asm volatile("s_waitcnt vmcnt(" #n ")" ::: "memory")
; #define PG8_WAIT_L(n) asm volatile("s_waitcnt lgkmcnt(" #n ")" ::: "memory")
; #define PG8_BAR __builtin_amdgcn_s_barrier()
; #define PG8_SCHED __builtin_amdgcn_sched_barrier(0)
; template <class Epi, class Sched, bool ALIGN_EPI = false, bool SP2 = false>
; __device__ __forceinline__ void gemm_phase(PG8_LAS unsigned char* lds, const Gemm g, const Sched& S, const Epi& E, const int tid) {
;     ...
;             PG8_LDA(At, 1, 1); PG8_STAGE(PG8_SB(1, 0), b3, voffB); PG8_STAGE(PG8_SB(1, 1), b3 + hstep, voffB); PG8_STAGE(PG8_SA(1, 0), a3, voffA);
;             PG8_WAIT_V(8); PG8_WAIT_L(0); PG8_BAR; PG8_MMA(1, 0, At, B0); PG8_MMA(1, 1, At, B1); PG8_BAR; PG8_SCHED;
	s_add_i32 s22, s52, s34
	v_lshl_add_u64 v[158:159], v[158:159], 0, s[28:29]
	s_mov_b32 m0, s22
	ds_read_b128 v[208:211], v149 offset:49152
	ds_read_b128 v[214:217], v149 offset:50176
	ds_read_b128 v[218:221], v149 offset:51200
	ds_read_b128 v[222:225], v149 offset:52224
	ds_read_b128 v[226:229], v149 offset:53248
	ds_read_b128 v[230:233], v149 offset:54272
	ds_read_b128 v[234:237], v149 offset:55296
	ds_read_b128 v[238:241], v149 offset:56320
	global_load_lds_dwordx4 v[158:159], off
	s_add_i32 m0, s22, 0x2000
	s_add_u32 s20, s20, 0x40080
	v_lshl_add_u64 v[158:159], v[174:175], 0, s[28:29]
	s_addc_u32 s21, s21, 0
	s_add_i32 s22, s53, s34
	global_load_lds_dwordx4 v[158:159], off
	v_lshl_add_u64 v[158:159], s[20:21], 0, v[160:161]
	s_mov_b32 m0, s22
	s_nop 0
	global_load_lds_dwordx4 v[158:159], off
	v_lshl_add_u64 v[158:159], s[20:21], 0, v[132:133]
	s_add_i32 m0, s22, 0x2000
	s_nop 0
	global_load_lds_dwordx4 v[158:159], off
	v_lshl_add_u64 v[158:159], v[178:179], 0, s[28:29]
	s_mov_b32 m0, s49
	s_nop 0
	global_load_lds_dwordx4 v[158:159], off
	v_lshl_add_u64 v[158:159], v[180:181], 0, s[28:29]
	s_mov_b32 m0, s50
	s_nop 0
	global_load_lds_dwordx4 v[158:159], off
	s_waitcnt vmcnt(8)
	s_waitcnt lgkmcnt(0)
	s_barrier
	s_setprio 1
	s_waitcnt lgkmcnt(0)
	v_mfma_f32_16x16x32_bf16 v[60:63], v[150:153], v[208:211], v[60:63]
	v_mfma_f32_16x16x32_bf16 v[52:55], v[162:165], v[208:211], v[52:55]
	v_mfma_f32_16x16x32_bf16 v[44:47], v[150:153], v[218:221], v[44:47]
	v_mfma_f32_16x16x32_bf16 v[36:39], v[162:165], v[218:221], v[36:39]
	v_mfma_f32_16x16x32_bf16 v[28:31], v[150:153], v[226:229], v[28:31]
	v_mfma_f32_16x16x32_bf16 v[20:23], v[162:165], v[226:229], v[20:23]
	v_mfma_f32_16x16x32_bf16 v[12:15], v[150:153], v[234:237], v[12:15]
	v_mfma_f32_16x16x32_bf16 v[4:7], v[162:165], v[234:237], v[4:7]
	v_mfma_f32_16x16x32_bf16 v[60:63], v[154:157], v[214:217], v[60:63]
	v_mfma_f32_16x16x32_bf16 v[52:55], v[166:169], v[214:217], v[52:55]
	v_mfma_f32_16x16x32_bf16 v[44:47], v[154:157], v[222:225], v[44:47]
	v_mfma_f32_16x16x32_bf16 v[36:39], v[166:169], v[222:225], v[36:39]
	v_mfma_f32_16x16x32_bf16 v[28:31], v[154:157], v[230:233], v[28:31]
	v_mfma_f32_16x16x32_bf16 v[20:23], v[166:169], v[230:233], v[20:23]
	v_mfma_f32_16x16x32_bf16 v[12:15], v[154:157], v[238:241], v[12:15]
	v_mfma_f32_16x16x32_bf16 v[4:7], v[166:169], v[238:241], v[4:7]
	s_setprio 0
	s_setprio 1
	v_mfma_f32_16x16x32_bf16 v[56:59], v[170:173], v[208:211], v[56:59]
	v_mfma_f32_16x16x32_bf16 v[48:51], v[188:191], v[208:211], v[48:51]
	v_mfma_f32_16x16x32_bf16 v[40:43], v[170:173], v[218:221], v[40:43]
	v_mfma_f32_16x16x32_bf16 v[32:35], v[188:191], v[218:221], v[32:35]
	v_mfma_f32_16x16x32_bf16 v[24:27], v[170:173], v[226:229], v[24:27]
	v_mfma_f32_16x16x32_bf16 v[16:19], v[188:191], v[226:229], v[16:19]
	v_mfma_f32_16x16x32_bf16 v[8:11], v[170:173], v[234:237], v[8:11]
	v_mfma_f32_16x16x32_bf16 v[0:3], v[188:191], v[234:237], v[0:3]
	v_mfma_f32_16x16x32_bf16 v[56:59], v[184:187], v[214:217], v[56:59]
	v_mfma_f32_16x16x32_bf16 v[48:51], v[192:195], v[214:217], v[48:51]
	v_mfma_f32_16x16x32_bf16 v[40:43], v[184:187], v[222:225], v[40:43]
	v_mfma_f32_16x16x32_bf16 v[32:35], v[192:195], v[222:225], v[32:35]
	v_mfma_f32_16x16x32_bf16 v[24:27], v[184:187], v[230:233], v[24:27]
	v_mfma_f32_16x16x32_bf16 v[16:19], v[192:195], v[230:233], v[16:19]
	v_mfma_f32_16x16x32_bf16 v[8:11], v[184:187], v[238:241], v[8:11]
	v_mfma_f32_16x16x32_bf16 v[0:3], v[192:195], v[238:241], v[0:3]
	s_setprio 0
	s_barrier
	s_add_i32 s51, s51, 2
	s_add_u32 s18, s18, 0x100
	s_addc_u32 s19, s19, 0
	s_add_u32 s42, s42, 0x100
	s_addc_u32 s43, s43, 0
	s_cmp_gt_u32 s51, 13
	s_cbranch_scc1 .Lmy_kdone_2
	.p2align	6

; #define PG8_STAGE(bufoff, gbase, voff) do { _Pragma("unroll") for (int _i = 0; _i < 2; ++_i) \
;         __builtin_amdgcn_global_load_lds((const unsigned*)((const char*)(gbase) + (voff)[_i]), (PG8_LAS unsigned*)(lds + (bufoff) + ldsw + _i * 8192), 16, 0, 0); } while (0)
; #define PG8_LDA(dst, b, h) do { _Pragma("unroll") for (int m = 0; m < 4; ++m) _Pragma("unroll") for (int k = 0; k < 2; ++k) dst[m][k] = *(const PG8_LAS bf16x8*)(lds + PG8_SA(b, h) + aoff + m * 2048 + k * 1024); } while (0)
; #define PG8_LDB(dst, b, h) do { _Pragma("unroll") for (int n = 0; n < 2; ++n) _Pragma("unroll") for (int k = 0; k < 2; ++k) dst[n][k] = *(const PG8_LAS bf16x8*)(lds + PG8_SB(b, h) + boff + n * 2048 + k * 1024); } while (0)
; #define PG8_WAIT_V(n) asm volatile("s_waitcnt vmcnt(" #n ")" ::: "memory")
; #define PG8_WAIT_L(n) asm volatile("s_waitcnt lgkmcnt(" #n ")" ::: "memory")
; #define PG8_BAR __builtin_amdgcn_s_barrier()
; #define PG8_SCHED __builtin_amdgcn_sched_barrier(0)
; template <class Epi, class Sched, bool ALIGN_EPI = false, bool SP2 = false>
; __device__ __forceinline__ void gemm_phase(PG8_LAS unsigned char* lds, const Gemm g, const Sched& S, const Epi& E, const int tid) {
;     ...
;         const bool has_next = S.next(ui + 1, nxt);
;         const char* nA = has_next ? (const char*)g.A + (size_t)nxt.pm * tstep : cA; const char* nB = has_next ? (const char*)g.Bt + (size_t)nxt.pn * tstep : cB;
;         for (int t = 0; t < nt; t += 2) {
;             const bool last = (t == nt - 2);
;             const char* a1 = cA + (size_t)(t + 1) * kstep;
;             const char* a2 = last ? nA : cA + (size_t)(t + 2) * kstep; const char* b2 = last ? nB : cB + (size_t)(t + 2) * kstep;
;             const char* a3 = a2 + kstep; const char* b3 = b2 + kstep;
;             if (last && has_next) S.a_ready(nxt);
;             if constexpr (SP2) {
;             PG8_LDB(B0, 0, 0); PG8_LDB(B1, 0, 1); PG8_SCHED; PG8_LDA(At, 0, 0); PG8_STAGE(PG8_SA(1, 1), a1 + hstep, voffA);
;             PG8_WAIT_V(8); PG8_WAIT_L(0); PG8_BAR; PG8_MMA(0, 0, At, B0); PG8_MMA(0, 1, At, B1); PG8_BAR; PG8_SCHED;
;             PG8_LDA(At, 0, 1); PG8_STAGE(PG8_SB(0, 0), b2, voffB); PG8_STAGE(PG8_SB(0, 1), b2 + hstep, voffB); PG8_STAGE(PG8_SA(0, 0), a2, voffA);
;             PG8_WAIT_V(8); PG8_WAIT_L(0); PG8_BAR; PG8_MMA(1, 0, At, B0); PG8_MMA(1, 1, At, B1); PG8_BAR; PG8_SCHED;
.LBB0_620:
	s_add_u32 s44, s50, 0x80
	s_addc_u32 s45, s51, 0
	s_add_u32 s37, s48, 0x100
	s_addc_u32 s50, s49, 0
	s_mov_b32 s48, 0
	s_add_i32 s51, s48, 2
	s_add_u32 vcc_lo, s44, 0x80
	s_addc_u32 s49, s45, 0
	s_cmp_eq_u32 s82, s48
	s_cselect_b32 s49, s35, s49
	s_cselect_b32 s48, s34, vcc_lo
	v_add_u32_e32 v156, s59, v174
	s_cselect_b32 vcc_hi, s47, s50
	s_cselect_b32 vcc_lo, s46, s37
	s_add_i32 s90, 0, 0x14000
	s_waitcnt lgkmcnt(0)
	ds_read_b128 v[144:147], v156
	ds_read_b128 v[148:151], v156 offset:1024
	ds_read_b128 v[152:155], v156 offset:2048
	ds_read_b128 v[184:187], v156 offset:3072
	v_add_u32_e32 v156, s90, v174
	ds_read_b128 v[188:191], v156
	ds_read_b128 v[192:195], v156 offset:1024
	ds_read_b128 v[214:217], v156 offset:2048
	ds_read_b128 v[218:221], v156 offset:3072
	v_lshl_add_u64 v[156:157], s[44:45], 0, v[140:141]
	s_add_i32 m0, s66, 0xc000
	ds_read_b128 v[222:225], v175
	ds_read_b128 v[226:229], v175 offset:1024
	ds_read_b128 v[230:233], v175 offset:2048
	ds_read_b128 v[234:237], v175 offset:3072
	ds_read_b128 v[238:241], v175 offset:4096
	ds_read_b128 v[242:245], v175 offset:5120
	ds_read_b128 v[246:249], v175 offset:6144
	ds_read_b128 v[208:211], v175 offset:7168
	global_load_lds_dwordx4 v[156:157], off
	v_lshl_add_u64 v[156:157], s[44:45], 0, v[142:143]
	s_add_i32 m0, s66, 0xe000
	s_nop 0
	global_load_lds_dwordx4 v[156:157], off
	s_waitcnt vmcnt(8)
	s_waitcnt lgkmcnt(0)
	s_barrier
	s_setprio 1
	s_waitcnt lgkmcnt(0)
	v_mfma_f32_16x16x32_bf16 v[124:127], v[144:147], v[222:225], 0
	v_mfma_f32_16x16x32_bf16 v[120:123], v[152:155], v[222:225], 0
	v_mfma_f32_16x16x32_bf16 v[108:111], v[144:147], v[230:233], 0
	v_mfma_f32_16x16x32_bf16 v[104:107], v[152:155], v[230:233], 0
	v_mfma_f32_16x16x32_bf16 v[92:95], v[144:147], v[238:241], 0
	v_mfma_f32_16x16x32_bf16 v[88:91], v[152:155], v[238:241], 0
	v_mfma_f32_16x16x32_bf16 v[76:79], v[144:147], v[246:249], 0
	v_mfma_f32_16x16x32_bf16 v[72:75], v[152:155], v[246:249], 0
	v_mfma_f32_16x16x32_bf16 v[124:127], v[148:151], v[226:229], v[124:127]
	v_mfma_f32_16x16x32_bf16 v[120:123], v[184:187], v[226:229], v[120:123]
	v_mfma_f32_16x16x32_bf16 v[108:111], v[148:151], v[234:237], v[108:111]
	v_mfma_f32_16x16x32_bf16 v[104:107], v[184:187], v[234:237], v[104:107]
	v_mfma_f32_16x16x32_bf16 v[92:95], v[148:151], v[242:245], v[92:95]
	v_mfma_f32_16x16x32_bf16 v[88:91], v[184:187], v[242:245], v[88:91]
	v_mfma_f32_16x16x32_bf16 v[76:79], v[148:151], v[208:211], v[76:79]
	v_mfma_f32_16x16x32_bf16 v[72:75], v[184:187], v[208:211], v[72:75]
	s_setprio 0
	s_setprio 1
	v_mfma_f32_16x16x32_bf16 v[116:119], v[188:191], v[222:225], 0
	v_mfma_f32_16x16x32_bf16 v[112:115], v[214:217], v[222:225], 0
	v_mfma_f32_16x16x32_bf16 v[100:103], v[188:191], v[230:233], 0
	v_mfma_f32_16x16x32_bf16 v[96:99], v[214:217], v[230:233], 0
	v_mfma_f32_16x16x32_bf16 v[84:87], v[188:191], v[238:241], 0
	v_mfma_f32_16x16x32_bf16 v[80:83], v[214:217], v[238:241], 0
	v_mfma_f32_16x16x32_bf16 v[68:71], v[188:191], v[246:249], 0
	v_mfma_f32_16x16x32_bf16 v[64:67], v[214:217], v[246:249], 0
	v_mfma_f32_16x16x32_bf16 v[116:119], v[192:195], v[226:229], v[116:119]
	v_mfma_f32_16x16x32_bf16 v[112:115], v[218:221], v[226:229], v[112:115]
	v_mfma_f32_16x16x32_bf16 v[100:103], v[192:195], v[234:237], v[100:103]
	v_mfma_f32_16x16x32_bf16 v[96:99], v[218:221], v[234:237], v[96:99]
	v_mfma_f32_16x16x32_bf16 v[84:87], v[192:195], v[242:245], v[84:87]
	v_mfma_f32_16x16x32_bf16 v[80:83], v[218:221], v[242:245], v[80:83]
	v_mfma_f32_16x16x32_bf16 v[68:71], v[192:195], v[208:211], v[68:71]
	v_mfma_f32_16x16x32_bf16 v[64:67], v[218:221], v[208:211], v[64:67]
	s_setprio 0
	s_barrier
	s_add_i32 s91, s59, s65
	v_lshl_add_u64 v[156:157], vcc, 0, v[160:161]
	s_mov_b32 m0, s91
	ds_read_b128 v[208:211], v175 offset:16384
	ds_read_b128 v[222:225], v175 offset:17408
	ds_read_b128 v[226:229], v175 offset:18432
	ds_read_b128 v[230:233], v175 offset:19456
	ds_read_b128 v[234:237], v175 offset:20480
	ds_read_b128 v[238:241], v175 offset:21504
	ds_read_b128 v[242:245], v175 offset:22528
	ds_read_b128 v[246:249], v175 offset:23552
	global_load_lds_dwordx4 v[156:157], off
	s_add_i32 m0, s91, 0x2000
	v_lshl_add_u64 v[250:251], vcc, 0, v[136:137]
	s_add_u32 vcc_lo, vcc_lo, s94
	s_addc_u32 vcc_hi, vcc_hi, 0
	s_add_i32 s90, s90, s65
	global_load_lds_dwordx4 v[250:251], off
	v_lshl_add_u64 v[178:179], vcc, 0, v[160:161]
	s_mov_b32 m0, s90
	v_lshl_add_u64 v[180:181], vcc, 0, v[136:137]
	global_load_lds_dwordx4 v[178:179], off
	s_add_i32 m0, s90, 0x2000
	v_lshl_add_u64 v[204:205], s[48:49], 0, v[132:133]
	global_load_lds_dwordx4 v[180:181], off
	s_mov_b32 m0, s66
	v_lshl_add_u64 v[196:197], s[48:49], 0, v[134:135]
	global_load_lds_dwordx4 v[204:205], off
	s_mov_b32 m0, s67
	s_nop 0
	global_load_lds_dwordx4 v[196:197], off
	s_waitcnt vmcnt(8)
	s_waitcnt lgkmcnt(0)
	s_barrier
; #define PG8_STAGE(bufoff, gbase, voff) do { _Pragma("unroll") for (int _i = 0; _i < 2; ++_i) \
;         __builtin_amdgcn_global_load_lds((const unsigned*)((const char*)(gbase) + (voff)[_i]), (PG8_LAS unsigned*)(lds + (bufoff) + ldsw + _i * 8192), 16, 0, 0); } while (0)
; #define PG8_LDA(dst, b, h) do { _Pragma("unroll") for (int m = 0; m < 4; ++m) _Pragma("unroll") for (int k = 0; k < 2; ++k) dst[m][k] = *(const PG8_LAS bf16x8*)(lds + PG8_SA(b, h) + aoff + m * 2048 + k * 1024); } while (0)
; #define PG8_LDB(dst, b, h) do { _Pragma("unroll") for (int n = 0; n < 2; ++n) _Pragma("unroll") for (int k = 0; k < 2; ++k) dst[n][k] = *(const PG8_LAS bf16x8*)(lds + PG8_SB(b, h) + boff + n * 2048 + k * 1024); } while (0)
; #define PG8_MMA(ai, bj, At, Bt) do { __builtin_amdgcn_s_setprio(1); _Pragma("unroll") for (int m = 0; m < 4; ++m) _Pragma("unroll") for (int n = 0; n < 2; ++n) _Pragma("unroll") for (int k = 0; k < 2; ++k) \
;         acc[ai][bj][m][n] = __builtin_amdgcn_mfma_f32_16x16x32_bf16(Bt[n][k], At[m][k], acc[ai][bj][m][n], 0, 0, 0); __builtin_amdgcn_s_setprio(0); } while (0)
; #define PG8_WAIT_V(n) asm volatile("s_waitcnt vmcnt(" #n ")" ::: "memory")
; #define PG8_WAIT_L(n) asm volatile("s_waitcnt lgkmcnt(" #n ")" ::: "memory")
; #define PG8_BAR __builtin_amdgcn_s_barrier()
; #define PG8_SCHED __builtin_amdgcn_sched_barrier(0)
; template <class Epi, class Sched, bool ALIGN_EPI = false, bool SP2 = false>
; __device__ __forceinline__ void gemm_phase(PG8_LAS unsigned char* lds, const Gemm g, const Sched& S, const Epi& E, const int tid) {
;     ...
;             PG8_WAIT_V(8); PG8_WAIT_L(0); PG8_BAR; PG8_MMA(1, 0, At, B0); PG8_MMA(1, 1, At, B1); PG8_BAR; PG8_SCHED;
;             PG8_LDB(B0, 1, 0); PG8_LDB(B1, 1, 1); PG8_SCHED; PG8_LDA(At, 1, 0); PG8_STAGE(PG8_SA(0, 1), a2 + hstep, voffA);
;             PG8_WAIT_V(8); PG8_WAIT_L(0); PG8_BAR; PG8_MMA(0, 0, At, B0); PG8_MMA(0, 1, At, B1); PG8_BAR; PG8_SCHED;
	s_setprio 1
	s_waitcnt lgkmcnt(0)
	v_mfma_f32_16x16x32_bf16 v[60:63], v[144:147], v[208:211], 0
	v_mfma_f32_16x16x32_bf16 v[56:59], v[152:155], v[208:211], 0
	v_mfma_f32_16x16x32_bf16 v[44:47], v[144:147], v[226:229], 0
	v_mfma_f32_16x16x32_bf16 v[40:43], v[152:155], v[226:229], 0
	v_mfma_f32_16x16x32_bf16 v[28:31], v[144:147], v[234:237], 0
	v_mfma_f32_16x16x32_bf16 v[24:27], v[152:155], v[234:237], 0
	v_mfma_f32_16x16x32_bf16 v[12:15], v[144:147], v[242:245], 0
	v_mfma_f32_16x16x32_bf16 v[8:11], v[152:155], v[242:245], 0
	v_mfma_f32_16x16x32_bf16 v[60:63], v[148:151], v[222:225], v[60:63]
	v_mfma_f32_16x16x32_bf16 v[56:59], v[184:187], v[222:225], v[56:59]
	v_mfma_f32_16x16x32_bf16 v[44:47], v[148:151], v[230:233], v[44:47]
	v_mfma_f32_16x16x32_bf16 v[40:43], v[184:187], v[230:233], v[40:43]
	v_mfma_f32_16x16x32_bf16 v[28:31], v[148:151], v[238:241], v[28:31]
	v_mfma_f32_16x16x32_bf16 v[24:27], v[184:187], v[238:241], v[24:27]
	v_mfma_f32_16x16x32_bf16 v[12:15], v[148:151], v[246:249], v[12:15]
	v_mfma_f32_16x16x32_bf16 v[8:11], v[184:187], v[246:249], v[8:11]
	s_setprio 0
	s_setprio 1
	v_mfma_f32_16x16x32_bf16 v[52:55], v[188:191], v[208:211], 0
	v_mfma_f32_16x16x32_bf16 v[48:51], v[214:217], v[208:211], 0
	v_mfma_f32_16x16x32_bf16 v[36:39], v[188:191], v[226:229], 0
	v_mfma_f32_16x16x32_bf16 v[32:35], v[214:217], v[226:229], 0
	v_mfma_f32_16x16x32_bf16 v[20:23], v[188:191], v[234:237], 0
	v_mfma_f32_16x16x32_bf16 v[16:19], v[214:217], v[234:237], 0
	v_mfma_f32_16x16x32_bf16 v[4:7], v[188:191], v[242:245], 0
	v_mfma_f32_16x16x32_bf16 v[0:3], v[214:217], v[242:245], 0
	v_mfma_f32_16x16x32_bf16 v[52:55], v[192:195], v[222:225], v[52:55]
	v_mfma_f32_16x16x32_bf16 v[48:51], v[218:221], v[222:225], v[48:51]
	v_mfma_f32_16x16x32_bf16 v[36:39], v[192:195], v[230:233], v[36:39]
	v_mfma_f32_16x16x32_bf16 v[32:35], v[218:221], v[230:233], v[32:35]
	v_mfma_f32_16x16x32_bf16 v[20:23], v[192:195], v[238:241], v[20:23]
	v_mfma_f32_16x16x32_bf16 v[16:19], v[218:221], v[238:241], v[16:19]
	v_mfma_f32_16x16x32_bf16 v[4:7], v[192:195], v[246:249], v[4:7]
	v_mfma_f32_16x16x32_bf16 v[0:3], v[218:221], v[246:249], v[0:3]
	s_setprio 0
	s_barrier
	s_add_i32 s90, 0, 0x18000
	v_add_u32_e32 v183, s90, v174
	s_add_i32 s91, 0, 0x1c000
	ds_read_b128 v[144:147], v183
	ds_read_b128 v[148:151], v183 offset:1024
	ds_read_b128 v[152:155], v183 offset:2048
	ds_read_b128 v[184:187], v183 offset:3072
	v_add_u32_e32 v183, s91, v174
	ds_read_b128 v[188:191], v183
	ds_read_b128 v[192:195], v183 offset:1024
	ds_read_b128 v[208:211], v183 offset:2048
	ds_read_b128 v[214:217], v183 offset:3072
	s_add_u32 s48, s48, s94
	s_addc_u32 s49, s49, 0
	s_mov_b32 m0, s68
	v_lshl_add_u64 v[198:199], s[48:49], 0, v[132:133]
	ds_read_b128 v[218:221], v175 offset:32768
	ds_read_b128 v[222:225], v175 offset:33792
	ds_read_b128 v[226:229], v175 offset:34816
	ds_read_b128 v[230:233], v175 offset:35840
	ds_read_b128 v[234:237], v175 offset:36864
	ds_read_b128 v[238:241], v175 offset:37888
	ds_read_b128 v[242:245], v175 offset:38912
	ds_read_b128 v[246:249], v175 offset:39936
	global_load_lds_dwordx4 v[198:199], off
	v_lshl_add_u64 v[198:199], s[48:49], 0, v[134:135]
	s_mov_b32 m0, s69
	s_nop 0
	global_load_lds_dwordx4 v[198:199], off
	s_waitcnt vmcnt(8)
	s_waitcnt lgkmcnt(0)
	s_barrier
	s_setprio 1
	s_waitcnt lgkmcnt(0)
	v_mfma_f32_16x16x32_bf16 v[124:127], v[144:147], v[218:221], v[124:127]
	v_mfma_f32_16x16x32_bf16 v[120:123], v[152:155], v[218:221], v[120:123]
	v_mfma_f32_16x16x32_bf16 v[108:111], v[144:147], v[226:229], v[108:111]
	v_mfma_f32_16x16x32_bf16 v[104:107], v[152:155], v[226:229], v[104:107]
	v_mfma_f32_16x16x32_bf16 v[92:95], v[144:147], v[234:237], v[92:95]
	v_mfma_f32_16x16x32_bf16 v[88:91], v[152:155], v[234:237], v[88:91]
	v_mfma_f32_16x16x32_bf16 v[76:79], v[144:147], v[242:245], v[76:79]
	v_mfma_f32_16x16x32_bf16 v[72:75], v[152:155], v[242:245], v[72:75]
	v_mfma_f32_16x16x32_bf16 v[124:127], v[148:151], v[222:225], v[124:127]
	v_mfma_f32_16x16x32_bf16 v[120:123], v[184:187], v[222:225], v[120:123]
	v_mfma_f32_16x16x32_bf16 v[108:111], v[148:151], v[230:233], v[108:111]
	v_mfma_f32_16x16x32_bf16 v[104:107], v[184:187], v[230:233], v[104:107]
	v_mfma_f32_16x16x32_bf16 v[92:95], v[148:151], v[238:241], v[92:95]
	v_mfma_f32_16x16x32_bf16 v[88:91], v[184:187], v[238:241], v[88:91]
	v_mfma_f32_16x16x32_bf16 v[76:79], v[148:151], v[246:249], v[76:79]
	v_mfma_f32_16x16x32_bf16 v[72:75], v[184:187], v[246:249], v[72:75]
	s_setprio 0
	s_setprio 1
	v_mfma_f32_16x16x32_bf16 v[116:119], v[188:191], v[218:221], v[116:119]
	v_mfma_f32_16x16x32_bf16 v[112:115], v[208:211], v[218:221], v[112:115]
	v_mfma_f32_16x16x32_bf16 v[100:103], v[188:191], v[226:229], v[100:103]
	v_mfma_f32_16x16x32_bf16 v[96:99], v[208:211], v[226:229], v[96:99]
	v_mfma_f32_16x16x32_bf16 v[84:87], v[188:191], v[234:237], v[84:87]
	v_mfma_f32_16x16x32_bf16 v[80:83], v[208:211], v[234:237], v[80:83]
	v_mfma_f32_16x16x32_bf16 v[68:71], v[188:191], v[242:245], v[68:71]
	v_mfma_f32_16x16x32_bf16 v[64:67], v[208:211], v[242:245], v[64:67]
	v_mfma_f32_16x16x32_bf16 v[116:119], v[192:195], v[222:225], v[116:119]
	v_mfma_f32_16x16x32_bf16 v[112:115], v[214:217], v[222:225], v[112:115]
	v_mfma_f32_16x16x32_bf16 v[100:103], v[192:195], v[230:233], v[100:103]
	v_mfma_f32_16x16x32_bf16 v[96:99], v[214:217], v[230:233], v[96:99]
	v_mfma_f32_16x16x32_bf16 v[84:87], v[192:195], v[238:241], v[84:87]
	v_mfma_f32_16x16x32_bf16 v[80:83], v[214:217], v[238:241], v[80:83]
	v_mfma_f32_16x16x32_bf16 v[68:71], v[192:195], v[246:249], v[68:71]
	v_mfma_f32_16x16x32_bf16 v[64:67], v[214:217], v[246:249], v[64:67]
	s_setprio 0
	s_barrier
; #define PG8_STAGE(bufoff, gbase, voff) do { _Pragma("unroll") for (int _i = 0; _i < 2; ++_i) \
;         __builtin_amdgcn_global_load_lds((const unsigned*)((const char*)(gbase) + (voff)[_i]), (PG8_LAS unsigned*)(lds + (bufoff) + ldsw + _i * 8192), 16, 0, 0); } while (0)
; #define PG8_LDA(dst, b, h) do { _Pragma("unroll") for (int m = 0; m < 4; ++m) _Pragma("unroll") for (int k = 0; k < 2; ++k) dst[m][k] = *(const PG8_LAS bf16x8*)(lds + PG8_SA(b, h) + aoff + m * 2048 + k * 1024); } while (0)
; #define PG8_MMA(ai, bj, At, Bt) do { __builtin_amdgcn_s_setprio(1); _Pragma("unroll") for (int m = 0; m < 4; ++m) _Pragma("unroll") for (int n = 0; n < 2; ++n) _Pragma("unroll") for (int k = 0; k < 2; ++k) \
;         acc[ai][bj][m][n] = __builtin_amdgcn_mfma_f32_16x16x32_bf16(Bt[n][k], At[m][k], acc[ai][bj][m][n], 0, 0, 0); __builtin_amdgcn_s_setprio(0); } while (0)
; #define PG8_WAIT_V(n) asm volatile("s_waitcnt vmcnt(" #n ")" ::: "memory")
; #define PG8_WAIT_L(n) asm volatile("s_waitcnt lgkmcnt(" #n ")" ::: "memory")
; #define PG8_BAR __builtin_amdgcn_s_barrier()
; #define PG8_SCHED __builtin_amdgcn_sched_barrier(0)
; template <class Epi, class Sched, bool ALIGN_EPI = false, bool SP2 = false>
; __device__ __forceinline__ void gemm_phase(PG8_LAS unsigned char* lds, const Gemm g, const Sched& S, const Epi& E, const int tid) {
;     ...
;             PG8_LDA(At, 1, 1); PG8_STAGE(PG8_SB(1, 0), b3, voffB); PG8_STAGE(PG8_SB(1, 1), b3 + hstep, voffB); PG8_STAGE(PG8_SA(1, 0), a3, voffA);
;             PG8_WAIT_V(8); PG8_WAIT_L(0); PG8_BAR; PG8_MMA(1, 0, At, B0); PG8_MMA(1, 1, At, B1); PG8_BAR; PG8_SCHED;
	s_add_i32 s48, s90, s65
	v_lshl_add_u64 v[156:157], v[156:157], 0, s[28:29]
	s_mov_b32 m0, s48
	ds_read_b128 v[218:221], v175 offset:49152
	ds_read_b128 v[222:225], v175 offset:50176
	ds_read_b128 v[226:229], v175 offset:51200
	ds_read_b128 v[230:233], v175 offset:52224
	ds_read_b128 v[234:237], v175 offset:53248
	ds_read_b128 v[238:241], v175 offset:54272
	ds_read_b128 v[242:245], v175 offset:55296
	ds_read_b128 v[246:249], v175 offset:56320
	global_load_lds_dwordx4 v[156:157], off
	v_lshl_add_u64 v[156:157], v[250:251], 0, s[28:29]
	s_add_i32 m0, s48, 0x2000
	s_add_i32 s48, s91, s65
	global_load_lds_dwordx4 v[156:157], off
	v_lshl_add_u64 v[156:157], v[178:179], 0, s[28:29]
	s_mov_b32 m0, s48
	s_nop 0
	global_load_lds_dwordx4 v[156:157], off
	v_lshl_add_u64 v[156:157], v[180:181], 0, s[28:29]
	s_add_i32 m0, s48, 0x2000
	s_nop 0
	global_load_lds_dwordx4 v[156:157], off
	v_lshl_add_u64 v[156:157], v[204:205], 0, s[28:29]
	s_mov_b32 m0, s70
	s_nop 0
	global_load_lds_dwordx4 v[156:157], off
	v_lshl_add_u64 v[156:157], v[196:197], 0, s[28:29]
	s_mov_b32 m0, s71
	s_nop 0
	global_load_lds_dwordx4 v[156:157], off
	s_waitcnt vmcnt(8)
	s_waitcnt lgkmcnt(0)
	s_barrier
	s_setprio 1
	s_waitcnt lgkmcnt(0)
	v_mfma_f32_16x16x32_bf16 v[60:63], v[144:147], v[218:221], v[60:63]
	v_mfma_f32_16x16x32_bf16 v[56:59], v[152:155], v[218:221], v[56:59]
	v_mfma_f32_16x16x32_bf16 v[44:47], v[144:147], v[226:229], v[44:47]
	v_mfma_f32_16x16x32_bf16 v[40:43], v[152:155], v[226:229], v[40:43]
	v_mfma_f32_16x16x32_bf16 v[28:31], v[144:147], v[234:237], v[28:31]
	v_mfma_f32_16x16x32_bf16 v[24:27], v[152:155], v[234:237], v[24:27]
	v_mfma_f32_16x16x32_bf16 v[12:15], v[144:147], v[242:245], v[12:15]
	v_mfma_f32_16x16x32_bf16 v[8:11], v[152:155], v[242:245], v[8:11]
	v_mfma_f32_16x16x32_bf16 v[60:63], v[148:151], v[222:225], v[60:63]
	v_mfma_f32_16x16x32_bf16 v[56:59], v[184:187], v[222:225], v[56:59]
	v_mfma_f32_16x16x32_bf16 v[44:47], v[148:151], v[230:233], v[44:47]
	v_mfma_f32_16x16x32_bf16 v[40:43], v[184:187], v[230:233], v[40:43]
	v_mfma_f32_16x16x32_bf16 v[28:31], v[148:151], v[238:241], v[28:31]
	v_mfma_f32_16x16x32_bf16 v[24:27], v[184:187], v[238:241], v[24:27]
	v_mfma_f32_16x16x32_bf16 v[12:15], v[148:151], v[246:249], v[12:15]
	v_mfma_f32_16x16x32_bf16 v[8:11], v[184:187], v[246:249], v[8:11]
	s_setprio 0
	s_setprio 1
	v_mfma_f32_16x16x32_bf16 v[52:55], v[188:191], v[218:221], v[52:55]
	v_mfma_f32_16x16x32_bf16 v[48:51], v[208:211], v[218:221], v[48:51]
	v_mfma_f32_16x16x32_bf16 v[36:39], v[188:191], v[226:229], v[36:39]
	v_mfma_f32_16x16x32_bf16 v[32:35], v[208:211], v[226:229], v[32:35]
	v_mfma_f32_16x16x32_bf16 v[20:23], v[188:191], v[234:237], v[20:23]
	v_mfma_f32_16x16x32_bf16 v[16:19], v[208:211], v[234:237], v[16:19]
	v_mfma_f32_16x16x32_bf16 v[4:7], v[188:191], v[242:245], v[4:7]
	v_mfma_f32_16x16x32_bf16 v[0:3], v[208:211], v[242:245], v[0:3]
	v_mfma_f32_16x16x32_bf16 v[52:55], v[192:195], v[222:225], v[52:55]
	v_mfma_f32_16x16x32_bf16 v[48:51], v[214:217], v[222:225], v[48:51]
	v_mfma_f32_16x16x32_bf16 v[36:39], v[192:195], v[230:233], v[36:39]
	v_mfma_f32_16x16x32_bf16 v[32:35], v[214:217], v[230:233], v[32:35]
	v_mfma_f32_16x16x32_bf16 v[20:23], v[192:195], v[238:241], v[20:23]
	v_mfma_f32_16x16x32_bf16 v[16:19], v[214:217], v[238:241], v[16:19]
	v_mfma_f32_16x16x32_bf16 v[4:7], v[192:195], v[246:249], v[4:7]
	v_mfma_f32_16x16x32_bf16 v[0:3], v[214:217], v[246:249], v[0:3]
	s_setprio 0
	s_barrier
	s_add_u32 s44, s44, 0x100
	s_addc_u32 s45, s45, 0
	s_add_u32 s37, s37, 0x100
	s_addc_u32 s50, s50, 0
	s_cmp_ge_u32 s51, s80
	s_mov_b32 s48, s51
	s_cbranch_scc1 .Lmy_kdone_3
	.p2align	6
